# attention score-accumulator init: 14 v_mov_b32 per tile replaced by 7 v_mov_b64 (on top of the LDS-DMA K/V staging)
# baseline (speedup 1.0000x reference)
; #define MFMA32(a, b, c) __builtin_amdgcn_mfma_f32_32x32x16_bf16((a), (b), (c), 0, 0, 0)
; #define SBAR() __builtin_amdgcn_sched_barrier(0)
; DI void qkt(f32x16& p0, f32x16& p1, const char* Ks, const bf16x8* qr, float negm, int r32, int hi) {
; #pragma unroll
;     for (int i = 0; i < 16; ++i) { p0[i] = negm; p1[i] = negm; }
; #pragma unroll
;     for (int d0 = 0; d0 < 8; ++d0) { const int cb = (d0 * 16 + hi * 8) * 2;
;         bf16x8 b0 = *(const bf16x8*)(Ks + KSWZ(r32, cb));
;         bf16x8 b1 = *(const bf16x8*)(Ks + KSWZ(32 + r32, cb));
;         p0 = MFMA32(b0, qr[d0], p0);
;         p1 = MFMA32(b1, qr[d0], p1); }
; }
; DI void attn_unit(const bf16_t* __restrict__ Qb, const bf16_t* __restrict__ Kh, const bf16_t* __restrict__ Vh, bf16_t* __restrict__ Ob, const float* __restrict__ onw, int seq, char* lds) {
;     ...
;     for (int j = 1; j + 1 < NT; j += 2) {
;         SBAR(); qkt(pB0, pB1, K_lds + SHM_K, qr, -m_reg, r32, hi);
;         finishSM(pA0, pA1, alA, l_reg, pa0, pa1, pa2, pa3); SBAR();
.LBB0_580:
	s_add_u32 m0, s100, 0x8000
	s_nop 0
	global_load_lds_dwordx4 v246, s[98:99]
	s_add_u32 m0, s100, 0xa000
	s_nop 0
	global_load_lds_dwordx4 v247, s[98:99]
	s_add_u32 m0, s100, 0x4000
	s_nop 0
	global_load_lds_dwordx4 v248, s[98:99]
	s_add_u32 m0, s100, 0x6000
	s_nop 0
	global_load_lds_dwordx4 v249, s[98:99]
	s_add_u32 s98, s98, 0x20000
	s_addc_u32 s99, s99, 0
	ds_read_b128 v[216:219], v183 offset:49152
	ds_read_b128 v[220:223], v183 offset:57344
	v_xor_b32_e32 v80, 0x80000000, v215
	v_mov_b32_e32 v81, v80
	v_mov_b64_e32 v[82:83], v[80:81]
	v_mov_b64_e32 v[84:85], v[80:81]
	v_mov_b64_e32 v[86:87], v[80:81]
	v_mov_b64_e32 v[88:89], v[80:81]
	v_mov_b64_e32 v[90:91], v[80:81]
	v_mov_b64_e32 v[92:93], v[80:81]
	v_mov_b64_e32 v[94:95], v[80:81]
	v_add_f32_e32 v144, 0, v166
	v_add_f32_e32 v144, v167, v144
	s_waitcnt lgkmcnt(1)
	v_mfma_f32_32x32x16_bf16 v[96:111], v[216:219], v[140:143], v[80:95]
	v_add_f32_e32 v144, v162, v144
	v_add_f32_e32 v144, v163, v144
	v_add_f32_e32 v144, v158, v144
	v_add_f32_e32 v144, v159, v144
	v_add_f32_e32 v144, v156, v144
	v_add_f32_e32 v144, v157, v144
	v_add_f32_e32 v144, v168, v144
	s_waitcnt lgkmcnt(0)
	v_mfma_f32_32x32x16_bf16 v[80:95], v[220:223], v[140:143], v[80:95]
	ds_read_b128 v[216:219], v208 offset:49152
	ds_read_b128 v[220:223], v208 offset:57344
	v_add_f32_e32 v144, v169, v144
	v_add_f32_e32 v144, v164, v144
	v_add_f32_e32 v144, v165, v144
	v_exp_f32_e32 v64, v64
	v_add_f32_e32 v144, v160, v144
	v_exp_f32_e32 v65, v65
	s_waitcnt lgkmcnt(0)
	v_mfma_f32_32x32x16_bf16 v[80:95], v[220:223], v[136:139], v[80:95]
	v_add_f32_e32 v144, v161, v144
	v_exp_f32_e32 v66, v66
	v_add_f32_e32 v144, v146, v144
	v_exp_f32_e32 v67, v67
	v_add_f32_e32 v144, v147, v144
	v_exp_f32_e32 v68, v68
	v_add_f32_e32 v144, v64, v144
	v_mfma_f32_32x32x16_bf16 v[96:111], v[216:219], v[136:139], v[96:111]
	ds_read_b128 v[216:219], v209 offset:49152
	ds_read_b128 v[220:223], v209 offset:57344
	v_exp_f32_e32 v69, v69
	v_add_f32_e32 v144, v65, v144
	v_exp_f32_e32 v70, v70
	v_add_f32_e32 v144, v66, v144
	v_exp_f32_e32 v71, v71
	v_add_f32_e32 v144, v67, v144
	s_waitcnt lgkmcnt(0)
	v_mfma_f32_32x32x16_bf16 v[80:95], v[220:223], v[132:135], v[80:95]
	v_exp_f32_e32 v72, v72
	v_add_f32_e32 v144, v68, v144
	v_exp_f32_e32 v73, v73
	v_add_f32_e32 v144, v69, v144
	v_exp_f32_e32 v74, v74
	v_add_f32_e32 v144, v70, v144
	v_exp_f32_e32 v75, v75
	v_mfma_f32_32x32x16_bf16 v[96:111], v[216:219], v[132:135], v[96:111]
	ds_read_b128 v[216:219], v210 offset:49152
	ds_read_b128 v[220:223], v210 offset:57344
	v_add_f32_e32 v144, v71, v144
	v_exp_f32_e32 v76, v76
	v_add_f32_e32 v144, v72, v144
	v_exp_f32_e32 v77, v77
	v_add_f32_e32 v144, v73, v144
	v_exp_f32_e32 v78, v78
	s_waitcnt lgkmcnt(0)
	v_mfma_f32_32x32x16_bf16 v[80:95], v[220:223], v[128:131], v[80:95]
	v_add_f32_e32 v144, v74, v144
	v_exp_f32_e32 v79, v79
	v_add_f32_e32 v144, v75, v144
	v_add_f32_e32 v144, v76, v144
	v_add_f32_e32 v144, v77, v144
	v_add_f32_e32 v144, v78, v144
	v_mfma_f32_32x32x16_bf16 v[96:111], v[216:219], v[128:131], v[96:111]
	ds_read_b128 v[216:219], v211 offset:49152
	ds_read_b128 v[220:223], v211 offset:57344
	s_waitcnt lgkmcnt(0)
	v_mfma_f32_32x32x16_bf16 v[80:95], v[220:223], v[124:127], v[80:95]
	v_mfma_f32_32x32x16_bf16 v[96:111], v[216:219], v[124:127], v[96:111]
	ds_read_b128 v[216:219], v212 offset:49152
	ds_read_b128 v[220:223], v212 offset:57344
	s_waitcnt lgkmcnt(0)
	v_mfma_f32_32x32x16_bf16 v[80:95], v[220:223], v[120:123], v[80:95]
	v_mfma_f32_32x32x16_bf16 v[96:111], v[216:219], v[120:123], v[96:111]
	ds_read_b128 v[216:219], v213 offset:49152
	ds_read_b128 v[220:223], v213 offset:57344
	s_waitcnt lgkmcnt(0)
	v_mfma_f32_32x32x16_bf16 v[80:95], v[220:223], v[116:119], v[80:95]
	v_mfma_f32_32x32x16_bf16 v[96:111], v[216:219], v[116:119], v[96:111]
	ds_read_b128 v[216:219], v214 offset:49152
	ds_read_b128 v[220:223], v214 offset:57344
	s_waitcnt lgkmcnt(0)
; #define MFMA32(a, b, c) __builtin_amdgcn_mfma_f32_32x32x16_bf16((a), (b), (c), 0, 0, 0)
; #define SBAR() __builtin_amdgcn_sched_barrier(0)
; template <int OFF> DI s16x4 tr_read(int vb) { s16x4 r; asm volatile("ds_read_b64_tr_b16 %0, %1 offset:%2" : "=&v"(r) : "v"(vb), "i"(OFF) : "memory"); return r; }
; #define SLOAD(i, k0) do { sr_[i].vs0 = *(const bf16x8*)(&Vh[(long)((k0) + sr) * LDA_ + sc]); sr_[i].vs1 = *(const bf16x8*)(&Vh[(long)((k0) + 32 + sr) * LDA_ + sc]); \
;     sr_[i].ks0 = *(const bf16x8*)(&Kh[(long)((k0) + sr) * LDA_ + sc]); sr_[i].ks1 = *(const bf16x8*)(&Kh[(long)((k0) + 32 + sr) * LDA_ + sc]); } while (0)
; template <int D0> DI void pv_one(f32x16& od, int vb, bf16x8 pa0, bf16x8 pa1, bf16x8 pa2, bf16x8 pa3) {
;     const s16x4 l0 = tr_read<v_rd_off(D0, 0, 0)>(vb), h0 = tr_read<v_rd_off(D0, 0, 1)>(vb), l1 = tr_read<v_rd_off(D0, 1, 0)>(vb), h1 = tr_read<v_rd_off(D0, 1, 1)>(vb);
;     const s16x4 l2 = tr_read<v_rd_off(D0, 2, 0)>(vb), h2 = tr_read<v_rd_off(D0, 2, 1)>(vb), l3 = tr_read<v_rd_off(D0, 3, 0)>(vb), h3 = tr_read<v_rd_off(D0, 3, 1)>(vb);
;     asm volatile("s_waitcnt lgkmcnt(0)" ::: "memory"); SBAR();
;     ...
;     od = MFMA32(pa0, PK(l0, h0), od);
;     od = MFMA32(pa1, PK(l1, h1), od);
;     od = MFMA32(pa2, PK(l2, h2), od);
;     od = MFMA32(pa3, PK(l3, h3), od);
;     ...
; }
; DI float pv_d0_sm(f32x16* o, int vb, bf16x8 pa0, bf16x8 pa1, bf16x8 pa2, bf16x8 pa3, f32x16& q0, f32x16& q1) {
;     pv_one<0>(o[0], vb, pa0, pa1, pa2, pa3); const float mx0 = smA_max0(q0);
;     pv_one<1>(o[1], vb, pa0, pa1, pa2, pa3); const float pmax = smA_max1(mx0, q1);
;     pv_one<2>(o[2], vb, pa0, pa1, pa2, pa3); smA_exp<0>(q0);
;     pv_one<3>(o[3], vb, pa0, pa1, pa2, pa3); smA_exp<8>(q0);
;     return pmax;
; }
; DI void attn_unit(const bf16_t* __restrict__ Qb, const bf16_t* __restrict__ Kh, const bf16_t* __restrict__ Vh, bf16_t* __restrict__ Ob, const float* __restrict__ onw, int seq, char* lds) {
;     ...
;         finishSM(pA0, pA1, alA, l_reg, pa0, pa1, pa2, pa3); SBAR();
;         SLOAD(SO, (j + 1) * 64); SBAR();
;         { const float pm = pv_d0_sm(o, vb0, pa0, pa1, pa2, pa3, pB0, pB1); smB<false>(pB0, pB1, pm, m_reg, alB); }
	v_mfma_f32_32x32x16_bf16 v[80:95], v[220:223], v[112:115], v[80:95]
	v_mfma_f32_32x32x16_bf16 v[96:111], v[216:219], v[112:115], v[96:111]
	v_add_f32_e32 v216, v79, v144
	v_mov_b32_e32 v217, v216
	v_cvt_pk_bf16_f32 v218, v166, v167
	v_cvt_pk_bf16_f32 v219, v162, v163
	v_cvt_pk_bf16_f32 v220, v158, v159
	v_cvt_pk_bf16_f32 v221, v156, v157
	v_cvt_pk_bf16_f32 v162, v168, v169
	v_cvt_pk_bf16_f32 v163, v164, v165
	v_cvt_pk_bf16_f32 v164, v160, v161
	v_cvt_pk_bf16_f32 v165, v146, v147
	s_nop 1
	v_permlane32_swap_b32_e32 v216, v217
	v_permlane32_swap_b32_e32 v162, v164
	v_permlane32_swap_b32_e32 v163, v165
	v_cvt_pk_bf16_f32 v222, v64, v65
	v_cvt_pk_bf16_f32 v223, v66, v67
	v_cvt_pk_bf16_f32 v224, v68, v69
	v_cvt_pk_bf16_f32 v225, v70, v71
	v_cvt_pk_bf16_f32 v226, v72, v73
	v_cvt_pk_bf16_f32 v227, v74, v75
	v_cvt_pk_bf16_f32 v228, v76, v77
	v_cvt_pk_bf16_f32 v229, v78, v79
	v_permlane32_swap_b32_e32 v218, v220
	v_permlane32_swap_b32_e32 v219, v221
	v_permlane32_swap_b32_e32 v222, v224
	v_permlane32_swap_b32_e32 v223, v225
	v_permlane32_swap_b32_e32 v226, v228
	v_permlane32_swap_b32_e32 v227, v229
	ds_read_b64_tr_b16 v[144:145], v175 offset:0
	ds_read_b64_tr_b16 v[146:147], v175 offset:0x800
	ds_read_b64_tr_b16 v[156:157], v175 offset:0x1000
	ds_read_b64_tr_b16 v[158:159], v175 offset:0x1800
	ds_read_b64_tr_b16 v[166:167], v175 offset:0x2000
	ds_read_b64_tr_b16 v[168:169], v175 offset:0x2800
	ds_read_b64_tr_b16 v[230:231], v175 offset:0x3000
	ds_read_b64_tr_b16 v[232:233], v175 offset:0x3800
	s_waitcnt lgkmcnt(0)
	s_nop 0
	v_mfma_f32_32x32x16_bf16 v[0:15], v[218:221], v[144:147], v[0:15]
	v_max_f32_e32 v144, v97, v97
	v_max_f32_e32 v145, v96, v96
	v_max_f32_e32 v144, v145, v144
	v_max3_f32 v144, v144, v98, v99
	v_max3_f32 v144, v144, v100, v101
	v_max3_f32 v144, v144, v102, v103
	v_max3_f32 v144, v144, v104, v105
	v_mfma_f32_32x32x16_bf16 v[0:15], v[162:165], v[156:159], v[0:15]
	v_max3_f32 v144, v144, v106, v107
	v_max3_f32 v146, v144, v108, v109
	ds_read_b64_tr_b16 v[144:145], v175 offset:0x200
	v_max3_f32 v154, v146, v110, v111
	ds_read_b64_tr_b16 v[146:147], v175 offset:0xa00
	ds_read_b64_tr_b16 v[156:157], v175 offset:0x1200
	ds_read_b64_tr_b16 v[158:159], v175 offset:0x1a00
	v_mfma_f32_32x32x16_bf16 v[0:15], v[222:225], v[166:169], v[0:15]
	ds_read_b64_tr_b16 v[234:235], v175 offset:0x2200
	ds_read_b64_tr_b16 v[236:237], v175 offset:0x2a00
	ds_read_b64_tr_b16 v[238:239], v175 offset:0x3200
	ds_read_b64_tr_b16 v[240:241], v175 offset:0x3a00
	s_waitcnt lgkmcnt(0)
	v_mfma_f32_32x32x16_bf16 v[0:15], v[226:229], v[230:233], v[0:15]
	v_mfma_f32_32x32x16_bf16 v[48:63], v[218:221], v[144:147], v[48:63]
	v_max3_f32 v154, v154, v80, v81
	v_max3_f32 v144, v154, v82, v83
	v_max3_f32 v144, v144, v84, v85
	v_max3_f32 v144, v144, v86, v87
	v_max3_f32 v144, v144, v88, v89
	v_max3_f32 v144, v144, v90, v91
	v_max3_f32 v144, v144, v92, v93
	v_mfma_f32_32x32x16_bf16 v[48:63], v[162:165], v[156:159], v[48:63]
	v_max3_f32 v144, v144, v94, v95
	v_mov_b32_e32 v145, v144
	s_nop 1
	v_permlane32_swap_b32_e32 v144, v145
	v_max_f32_e32 v145, v145, v145
	v_max_f32_e32 v144, v144, v144
	v_max_f32_e32 v168, v144, v145
	v_mfma_f32_32x32x16_bf16 v[48:63], v[222:225], v[234:237], v[48:63]
	ds_read_b64_tr_b16 v[144:145], v175 offset:0x400
	ds_read_b64_tr_b16 v[146:147], v175 offset:0xc00
	ds_read_b64_tr_b16 v[156:157], v175 offset:0x1400
	ds_read_b64_tr_b16 v[158:159], v175 offset:0x1c00
	ds_read_b64_tr_b16 v[230:231], v175 offset:0x2400
	ds_read_b64_tr_b16 v[232:233], v175 offset:0x2c00
	ds_read_b64_tr_b16 v[234:235], v175 offset:0x3400
	v_mfma_f32_32x32x16_bf16 v[48:63], v[226:229], v[238:241], v[48:63]
	ds_read_b64_tr_b16 v[236:237], v175 offset:0x3c00
	s_waitcnt lgkmcnt(0)
	v_mfma_f32_32x32x16_bf16 v[16:31], v[218:221], v[144:147], v[16:31]
	v_exp_f32_e32 v144, v96
	v_exp_f32_e32 v145, v97
	ds_read_b64_tr_b16 v[96:97], v175 offset:0x600
	v_exp_f32_e32 v146, v100
	v_exp_f32_e32 v147, v101
	v_mfma_f32_32x32x16_bf16 v[16:31], v[162:165], v[156:159], v[16:31]
	v_exp_f32_e32 v158, v98
	v_exp_f32_e32 v159, v99
	ds_read_b64_tr_b16 v[98:99], v175 offset:0xe00
	ds_read_b64_tr_b16 v[100:101], v175 offset:0x1600
	v_exp_f32_e32 v156, v102
	v_exp_f32_e32 v157, v103
	ds_read_b64_tr_b16 v[102:103], v175 offset:0x1e00
	v_mfma_f32_32x32x16_bf16 v[16:31], v[222:225], v[230:233], v[16:31]
	ds_read_b64_tr_b16 v[230:231], v175 offset:0x2600
	ds_read_b64_tr_b16 v[232:233], v175 offset:0x2e00
	ds_read_b64_tr_b16 v[238:239], v175 offset:0x3600
	ds_read_b64_tr_b16 v[240:241], v175 offset:0x3e00
	s_waitcnt lgkmcnt(0)
	v_mfma_f32_32x32x16_bf16 v[16:31], v[226:229], v[234:237], v[16:31]
	v_mfma_f32_32x32x16_bf16 v[32:47], v[218:221], v[96:99], v[32:47]
	v_exp_f32_e32 v166, v104
	v_exp_f32_e32 v167, v105
	v_exp_f32_e32 v160, v110
	v_exp_f32_e32 v161, v111
	v_cmp_ge_f32_e32 vcc, s82, v168
	v_mov_b32_e32 v154, 1.0
	s_cmp_eq_u64 vcc, exec
	v_mfma_f32_32x32x16_bf16 v[32:47], v[162:165], v[100:103], v[32:47]
	v_exp_f32_e32 v162, v106
	v_exp_f32_e32 v163, v107
	v_exp_f32_e32 v164, v108
	v_exp_f32_e32 v165, v109
	v_mfma_f32_32x32x16_bf16 v[32:47], v[222:225], v[230:233], v[32:47]
	v_mfma_f32_32x32x16_bf16 v[32:47], v[226:229], v[238:241], v[32:47]
	s_cbranch_scc0 .LBB0_593

; #define MFMA32(a, b, c) __builtin_amdgcn_mfma_f32_32x32x16_bf16((a), (b), (c), 0, 0, 0)
; #define SBAR() __builtin_amdgcn_sched_barrier(0)
; DI void qkt(f32x16& p0, f32x16& p1, const char* Ks, const bf16x8* qr, float negm, int r32, int hi) {
; #pragma unroll
;     for (int i = 0; i < 16; ++i) { p0[i] = negm; p1[i] = negm; }
; #pragma unroll
;     for (int d0 = 0; d0 < 8; ++d0) { const int cb = (d0 * 16 + hi * 8) * 2;
;         bf16x8 b0 = *(const bf16x8*)(Ks + KSWZ(r32, cb));
;         bf16x8 b1 = *(const bf16x8*)(Ks + KSWZ(32 + r32, cb));
;         p0 = MFMA32(b0, qr[d0], p0);
;         p1 = MFMA32(b1, qr[d0], p1); }
; }
; DI void attn_unit(const bf16_t* __restrict__ Qb, const bf16_t* __restrict__ Kh, const bf16_t* __restrict__ Vh, bf16_t* __restrict__ Ob, const float* __restrict__ onw, int seq, char* lds) {
;     ...
;         SBAR(); qkt(pA0, pA1, K_lds, qr, -m_reg, r32, hi);
;         finishSM(pB0, pB1, alB, l_reg, pa0, pa1, pa2, pa3); SBAR();
.LBB0_585:
	ds_read_b128 v[218:221], v183 offset:32768
	ds_read_b128 v[222:225], v183 offset:40960
	v_xor_b32_e32 v64, 0x80000000, v215
	v_mov_b32_e32 v65, v64
	v_mov_b64_e32 v[66:67], v[64:65]
	v_mov_b64_e32 v[68:69], v[64:65]
	v_mov_b64_e32 v[70:71], v[64:65]
	v_mov_b64_e32 v[72:73], v[64:65]
	v_mov_b64_e32 v[74:75], v[64:65]
	v_mov_b64_e32 v[76:77], v[64:65]
	v_mov_b64_e32 v[78:79], v[64:65]
	v_add_f32_e32 v168, 0, v144
	v_add_f32_e32 v168, v145, v168
	s_waitcnt lgkmcnt(1)
	v_mfma_f32_32x32x16_bf16 v[96:111], v[218:221], v[140:143], v[64:79]
	v_add_f32_e32 v168, v158, v168
	v_add_f32_e32 v168, v159, v168
	v_add_f32_e32 v168, v146, v168
	v_add_f32_e32 v168, v147, v168
	v_add_f32_e32 v168, v156, v168
	v_add_f32_e32 v168, v157, v168
	v_add_f32_e32 v168, v166, v168
	s_waitcnt lgkmcnt(0)
	v_mfma_f32_32x32x16_bf16 v[64:79], v[222:225], v[140:143], v[64:79]
	ds_read_b128 v[218:221], v208 offset:32768
	ds_read_b128 v[222:225], v208 offset:40960
	v_add_f32_e32 v168, v167, v168
	v_add_f32_e32 v168, v162, v168
	v_add_f32_e32 v168, v163, v168
	v_exp_f32_e32 v80, v80
	v_add_f32_e32 v168, v164, v168
	v_exp_f32_e32 v81, v81
	s_waitcnt lgkmcnt(0)
	v_mfma_f32_32x32x16_bf16 v[64:79], v[222:225], v[136:139], v[64:79]
	v_add_f32_e32 v168, v165, v168
	v_exp_f32_e32 v82, v82
	v_add_f32_e32 v168, v160, v168
	v_exp_f32_e32 v83, v83
	v_add_f32_e32 v168, v161, v168
	v_exp_f32_e32 v84, v84
	v_add_f32_e32 v168, v80, v168
	v_mfma_f32_32x32x16_bf16 v[96:111], v[218:221], v[136:139], v[96:111]
	ds_read_b128 v[218:221], v209 offset:32768
	ds_read_b128 v[222:225], v209 offset:40960
	v_exp_f32_e32 v85, v85
	v_add_f32_e32 v168, v81, v168
	v_exp_f32_e32 v86, v86
	v_add_f32_e32 v168, v82, v168
	v_exp_f32_e32 v87, v87
	v_add_f32_e32 v168, v83, v168
	s_waitcnt lgkmcnt(0)
	v_mfma_f32_32x32x16_bf16 v[64:79], v[222:225], v[132:135], v[64:79]
	v_exp_f32_e32 v88, v88
	v_add_f32_e32 v168, v84, v168
	v_exp_f32_e32 v89, v89
	v_add_f32_e32 v168, v85, v168
	v_exp_f32_e32 v90, v90
	v_add_f32_e32 v168, v86, v168
	v_exp_f32_e32 v91, v91
	v_mfma_f32_32x32x16_bf16 v[96:111], v[218:221], v[132:135], v[96:111]
	ds_read_b128 v[218:221], v210 offset:32768
	ds_read_b128 v[222:225], v210 offset:40960
	v_add_f32_e32 v168, v87, v168
	v_exp_f32_e32 v92, v92
	v_add_f32_e32 v168, v88, v168
	v_exp_f32_e32 v93, v93
	v_add_f32_e32 v168, v89, v168
	v_exp_f32_e32 v94, v94
	s_waitcnt lgkmcnt(0)
	v_mfma_f32_32x32x16_bf16 v[64:79], v[222:225], v[128:131], v[64:79]
	v_add_f32_e32 v168, v90, v168
	v_exp_f32_e32 v95, v95
	v_add_f32_e32 v168, v91, v168
	v_add_f32_e32 v168, v92, v168
	v_add_f32_e32 v168, v93, v168
	v_add_f32_e32 v168, v94, v168
	v_mfma_f32_32x32x16_bf16 v[96:111], v[218:221], v[128:131], v[96:111]
	ds_read_b128 v[218:221], v211 offset:32768
	ds_read_b128 v[222:225], v211 offset:40960
	s_waitcnt lgkmcnt(0)
	v_mfma_f32_32x32x16_bf16 v[64:79], v[222:225], v[124:127], v[64:79]
	v_mfma_f32_32x32x16_bf16 v[96:111], v[218:221], v[124:127], v[96:111]
	ds_read_b128 v[218:221], v212 offset:32768
	ds_read_b128 v[222:225], v212 offset:40960
	s_waitcnt lgkmcnt(0)
	v_mfma_f32_32x32x16_bf16 v[64:79], v[222:225], v[120:123], v[64:79]
	v_mfma_f32_32x32x16_bf16 v[96:111], v[218:221], v[120:123], v[96:111]
	ds_read_b128 v[218:221], v213 offset:32768
	ds_read_b128 v[222:225], v213 offset:40960
	s_waitcnt lgkmcnt(0)
	v_mfma_f32_32x32x16_bf16 v[64:79], v[222:225], v[116:119], v[64:79]
	v_mfma_f32_32x32x16_bf16 v[96:111], v[218:221], v[116:119], v[96:111]
	ds_read_b128 v[218:221], v214 offset:32768
	ds_read_b128 v[222:225], v214 offset:40960
	v_cvt_pk_bf16_f32 v144, v144, v145
	v_cvt_pk_bf16_f32 v145, v158, v159
	v_cvt_pk_bf16_f32 v146, v146, v147
	v_cvt_pk_bf16_f32 v147, v156, v157
	s_nop 0
	v_permlane32_swap_b32_e32 v144, v146
	s_waitcnt lgkmcnt(0)
; #define MFMA32(a, b, c) __builtin_amdgcn_mfma_f32_32x32x16_bf16((a), (b), (c), 0, 0, 0)
; #define SBAR() __builtin_amdgcn_sched_barrier(0)
; template <int OFF> DI s16x4 tr_read(int vb) { s16x4 r; asm volatile("ds_read_b64_tr_b16 %0, %1 offset:%2" : "=&v"(r) : "v"(vb), "i"(OFF) : "memory"); return r; }
; #define SLOAD(i, k0) do { sr_[i].vs0 = *(const bf16x8*)(&Vh[(long)((k0) + sr) * LDA_ + sc]); sr_[i].vs1 = *(const bf16x8*)(&Vh[(long)((k0) + 32 + sr) * LDA_ + sc]); \
;     sr_[i].ks0 = *(const bf16x8*)(&Kh[(long)((k0) + sr) * LDA_ + sc]); sr_[i].ks1 = *(const bf16x8*)(&Kh[(long)((k0) + 32 + sr) * LDA_ + sc]); } while (0)
; template <int D0> DI void pv_one(f32x16& od, int vb, bf16x8 pa0, bf16x8 pa1, bf16x8 pa2, bf16x8 pa3) {
;     const s16x4 l0 = tr_read<v_rd_off(D0, 0, 0)>(vb), h0 = tr_read<v_rd_off(D0, 0, 1)>(vb), l1 = tr_read<v_rd_off(D0, 1, 0)>(vb), h1 = tr_read<v_rd_off(D0, 1, 1)>(vb);
;     const s16x4 l2 = tr_read<v_rd_off(D0, 2, 0)>(vb), h2 = tr_read<v_rd_off(D0, 2, 1)>(vb), l3 = tr_read<v_rd_off(D0, 3, 0)>(vb), h3 = tr_read<v_rd_off(D0, 3, 1)>(vb);
;     asm volatile("s_waitcnt lgkmcnt(0)" ::: "memory"); SBAR();
;     ...
;     od = MFMA32(pa0, PK(l0, h0), od);
;     od = MFMA32(pa1, PK(l1, h1), od);
;     od = MFMA32(pa2, PK(l2, h2), od);
;     od = MFMA32(pa3, PK(l3, h3), od);
;     ...
; }
; DI float pv_d0_sm(f32x16* o, int vb, bf16x8 pa0, bf16x8 pa1, bf16x8 pa2, bf16x8 pa3, f32x16& q0, f32x16& q1) {
;     pv_one<0>(o[0], vb, pa0, pa1, pa2, pa3); const float mx0 = smA_max0(q0);
;     pv_one<1>(o[1], vb, pa0, pa1, pa2, pa3); const float pmax = smA_max1(mx0, q1);
;     pv_one<2>(o[2], vb, pa0, pa1, pa2, pa3); smA_exp<0>(q0);
;     pv_one<3>(o[3], vb, pa0, pa1, pa2, pa3); smA_exp<8>(q0);
;     return pmax;
; }
; DI void attn_unit(const bf16_t* __restrict__ Qb, const bf16_t* __restrict__ Kh, const bf16_t* __restrict__ Vh, bf16_t* __restrict__ Ob, const float* __restrict__ onw, int seq, char* lds) {
;     ...
;         finishSM(pB0, pB1, alB, l_reg, pa0, pa1, pa2, pa3); SBAR();
;         SLOAD(SE, (j + 2) * 64); SBAR();
;         { const float pm = pv_d0_sm(o, vb0 + (int)SHM_V, pa0, pa1, pa2, pa3, pA0, pA1); smB<false>(pA0, pA1, pm, m_reg, alA); }
	v_mfma_f32_32x32x16_bf16 v[64:79], v[222:225], v[112:115], v[64:79]
	v_permlane32_swap_b32_e32 v145, v147
	v_cvt_pk_bf16_f32 v222, v166, v167
	v_cvt_pk_bf16_f32 v223, v162, v163
	v_cvt_pk_bf16_f32 v224, v164, v165
	v_cvt_pk_bf16_f32 v225, v160, v161
	v_cvt_pk_bf16_f32 v226, v80, v81
	v_mfma_f32_32x32x16_bf16 v[96:111], v[218:221], v[112:115], v[96:111]
	v_add_f32_e32 v218, v95, v168
	v_mov_b32_e32 v219, v218
	s_nop 1
	v_permlane32_swap_b32_e32 v218, v219
	v_cvt_pk_bf16_f32 v227, v82, v83
	v_cvt_pk_bf16_f32 v228, v84, v85
	v_cvt_pk_bf16_f32 v229, v86, v87
	v_cvt_pk_bf16_f32 v230, v88, v89
	v_cvt_pk_bf16_f32 v231, v90, v91
	v_cvt_pk_bf16_f32 v232, v92, v93
	v_cvt_pk_bf16_f32 v233, v94, v95
	v_permlane32_swap_b32_e32 v222, v224
	v_permlane32_swap_b32_e32 v223, v225
	v_permlane32_swap_b32_e32 v226, v228
	v_permlane32_swap_b32_e32 v227, v229
	v_permlane32_swap_b32_e32 v230, v232
	v_permlane32_swap_b32_e32 v231, v233
	ds_read_b64_tr_b16 v[156:157], v174 offset:0
	ds_read_b64_tr_b16 v[158:159], v174 offset:0x800
	ds_read_b64_tr_b16 v[160:161], v174 offset:0x1000
	ds_read_b64_tr_b16 v[162:163], v174 offset:0x1800
	ds_read_b64_tr_b16 v[164:165], v174 offset:0x2000
	ds_read_b64_tr_b16 v[166:167], v174 offset:0x2800
	ds_read_b64_tr_b16 v[234:235], v174 offset:0x3000
	ds_read_b64_tr_b16 v[236:237], v174 offset:0x3800
	s_waitcnt lgkmcnt(0)
	s_nop 0
	v_mfma_f32_32x32x16_bf16 v[0:15], v[144:147], v[156:159], v[0:15]
	v_max_f32_e32 v156, v97, v97
	v_max_f32_e32 v157, v96, v96
	v_max_f32_e32 v156, v157, v156
	v_max3_f32 v156, v156, v98, v99
	v_max3_f32 v156, v156, v100, v101
	v_max3_f32 v156, v156, v102, v103
	v_max3_f32 v156, v156, v104, v105
	v_mfma_f32_32x32x16_bf16 v[0:15], v[222:225], v[160:163], v[0:15]
	v_max3_f32 v156, v156, v106, v107
	v_max3_f32 v158, v156, v108, v109
	ds_read_b64_tr_b16 v[156:157], v174 offset:0x200
	v_max3_f32 v168, v158, v110, v111
	ds_read_b64_tr_b16 v[158:159], v174 offset:0xa00
	ds_read_b64_tr_b16 v[160:161], v174 offset:0x1200
	ds_read_b64_tr_b16 v[162:163], v174 offset:0x1a00
	v_mfma_f32_32x32x16_bf16 v[0:15], v[226:229], v[164:167], v[0:15]
	ds_read_b64_tr_b16 v[164:165], v174 offset:0x2200
	ds_read_b64_tr_b16 v[166:167], v174 offset:0x2a00
	ds_read_b64_tr_b16 v[238:239], v174 offset:0x3200
	ds_read_b64_tr_b16 v[240:241], v174 offset:0x3a00
	s_waitcnt lgkmcnt(0)
	v_mfma_f32_32x32x16_bf16 v[0:15], v[230:233], v[234:237], v[0:15]
	v_mfma_f32_32x32x16_bf16 v[48:63], v[144:147], v[156:159], v[48:63]
	v_max3_f32 v168, v168, v64, v65
	v_max3_f32 v156, v168, v66, v67
	v_max3_f32 v156, v156, v68, v69
	v_max3_f32 v156, v156, v70, v71
	v_max3_f32 v156, v156, v72, v73
	v_max3_f32 v156, v156, v74, v75
	v_max3_f32 v156, v156, v76, v77
	v_mfma_f32_32x32x16_bf16 v[48:63], v[222:225], v[160:163], v[48:63]
	v_max3_f32 v156, v156, v78, v79
	v_mov_b32_e32 v157, v156
	s_nop 1
	v_permlane32_swap_b32_e32 v156, v157
	v_max_f32_e32 v157, v157, v157
	v_max_f32_e32 v156, v156, v156
	v_max_f32_e32 v220, v156, v157
	v_mfma_f32_32x32x16_bf16 v[48:63], v[226:229], v[164:167], v[48:63]
	ds_read_b64_tr_b16 v[156:157], v174 offset:0x400
	ds_read_b64_tr_b16 v[158:159], v174 offset:0xc00
	ds_read_b64_tr_b16 v[160:161], v174 offset:0x1400
	ds_read_b64_tr_b16 v[162:163], v174 offset:0x1c00
	ds_read_b64_tr_b16 v[234:235], v174 offset:0x2400
	ds_read_b64_tr_b16 v[236:237], v174 offset:0x2c00
	ds_read_b64_tr_b16 v[242:243], v174 offset:0x3400
	v_mfma_f32_32x32x16_bf16 v[48:63], v[230:233], v[238:241], v[48:63]
	ds_read_b64_tr_b16 v[244:245], v174 offset:0x3c00
	s_waitcnt lgkmcnt(0)
	v_mfma_f32_32x32x16_bf16 v[16:31], v[144:147], v[156:159], v[16:31]
	v_exp_f32_e32 v166, v96
	v_exp_f32_e32 v167, v97
	ds_read_b64_tr_b16 v[96:97], v174 offset:0x600
	v_exp_f32_e32 v158, v100
	v_exp_f32_e32 v159, v101
	v_exp_f32_e32 v156, v102
	v_exp_f32_e32 v157, v103
	v_mfma_f32_32x32x16_bf16 v[16:31], v[222:225], v[160:163], v[16:31]
	v_exp_f32_e32 v162, v98
	v_exp_f32_e32 v163, v99
	ds_read_b64_tr_b16 v[98:99], v174 offset:0xe00
	ds_read_b64_tr_b16 v[100:101], v174 offset:0x1600
	ds_read_b64_tr_b16 v[102:103], v174 offset:0x1e00
	v_mfma_f32_32x32x16_bf16 v[16:31], v[226:229], v[234:237], v[16:31]
	ds_read_b64_tr_b16 v[234:235], v174 offset:0x2600
	ds_read_b64_tr_b16 v[236:237], v174 offset:0x2e00
	ds_read_b64_tr_b16 v[238:239], v174 offset:0x3600
	ds_read_b64_tr_b16 v[240:241], v174 offset:0x3e00
	s_waitcnt lgkmcnt(0)
	v_mfma_f32_32x32x16_bf16 v[16:31], v[230:233], v[242:245], v[16:31]
	v_mfma_f32_32x32x16_bf16 v[32:47], v[144:147], v[96:99], v[32:47]
	v_exp_f32_e32 v168, v104
	v_exp_f32_e32 v169, v105
	v_exp_f32_e32 v164, v106
	v_exp_f32_e32 v165, v107
	v_exp_f32_e32 v160, v108
	v_exp_f32_e32 v161, v109
	v_exp_f32_e32 v146, v110
	v_mfma_f32_32x32x16_bf16 v[32:47], v[222:225], v[100:103], v[32:47]
	v_exp_f32_e32 v147, v111
	v_cmp_ge_f32_e32 vcc, s82, v220
	s_cmp_eq_u64 vcc, exec
	v_mfma_f32_32x32x16_bf16 v[32:47], v[226:229], v[234:237], v[32:47]
	v_mfma_f32_32x32x16_bf16 v[32:47], v[230:233], v[238:241], v[32:47]
	s_cbranch_scc0 .LBB0_594
	v_mov_b32_e32 v144, 1.0

; #define MFMA32(a, b, c) __builtin_amdgcn_mfma_f32_32x32x16_bf16((a), (b), (c), 0, 0, 0)
; #define SBAR() __builtin_amdgcn_sched_barrier(0)
; DI void qkt(f32x16& p0, f32x16& p1, const char* Ks, const bf16x8* qr, float negm, int r32, int hi) {
; #pragma unroll
;     for (int i = 0; i < 16; ++i) { p0[i] = negm; p1[i] = negm; }
; #pragma unroll
;     for (int d0 = 0; d0 < 8; ++d0) { const int cb = (d0 * 16 + hi * 8) * 2;
;         bf16x8 b0 = *(const bf16x8*)(Ks + KSWZ(r32, cb));
;         bf16x8 b1 = *(const bf16x8*)(Ks + KSWZ(32 + r32, cb));
;         p0 = MFMA32(b0, qr[d0], p0);
;         p1 = MFMA32(b1, qr[d0], p1); }
; }
; DI void attn_unit(const bf16_t* __restrict__ Qb, const bf16_t* __restrict__ Kh, const bf16_t* __restrict__ Vh, bf16_t* __restrict__ Ob, const float* __restrict__ onw, int seq, char* lds) {
;     ...
;     SBAR(); qkt(pB0, pB1, K_lds + SHM_K, qr, -m_reg, r32, hi);
;     finishSM(pA0, pA1, alA, l_reg, pa0, pa1, pa2, pa3); SBAR();
;     { const float pm = pv_d0_sm(o, vb0, pa0, pa1, pa2, pa3, pB0, pB1); smB<false>(pB0, pB1, pm, m_reg, alB); }
.LBB0_595:
	s_add_u32 m0, s100, 0x4000
	s_nop 0
	global_load_lds_dwordx4 v248, s[98:99]
	s_add_u32 m0, s100, 0x6000
	s_nop 0
	global_load_lds_dwordx4 v249, s[98:99]
	ds_read_b128 v[204:207], v183 offset:49152
	ds_read_b128 v[216:219], v183 offset:57344
	v_xor_b32_e32 v80, 0x80000000, v215
	v_mov_b32_e32 v81, v80
	v_mov_b64_e32 v[82:83], v[80:81]
	v_mov_b64_e32 v[84:85], v[80:81]
	v_mov_b64_e32 v[86:87], v[80:81]
	v_mov_b64_e32 v[88:89], v[80:81]
	v_mov_b64_e32 v[90:91], v[80:81]
	v_mov_b64_e32 v[92:93], v[80:81]
	v_mov_b64_e32 v[94:95], v[80:81]
	v_exp_f32_e32 v145, v65
	v_add_f32_e32 v65, 0, v166
	s_waitcnt lgkmcnt(1)
	v_mfma_f32_32x32x16_bf16 v[96:111], v[204:207], v[140:143], v[80:95]
	v_add_f32_e32 v65, v167, v65
	v_add_f32_e32 v65, v162, v65
	v_add_f32_e32 v65, v163, v65
	v_add_f32_e32 v65, v158, v65
	v_add_f32_e32 v65, v159, v65
	v_add_f32_e32 v65, v156, v65
	v_add_f32_e32 v65, v157, v65
	s_waitcnt lgkmcnt(0)
	v_mfma_f32_32x32x16_bf16 v[80:95], v[216:219], v[140:143], v[80:95]
	ds_read_b128 v[140:143], v208 offset:49152
	ds_read_b128 v[204:207], v208 offset:57344
	v_add_f32_e32 v65, v168, v65
	v_add_f32_e32 v65, v169, v65
	v_add_f32_e32 v65, v164, v65
	v_add_f32_e32 v65, v165, v65
	v_exp_f32_e32 v64, v64
	v_add_f32_e32 v65, v160, v65
	s_waitcnt lgkmcnt(1)
	v_mfma_f32_32x32x16_bf16 v[96:111], v[140:143], v[136:139], v[96:111]
	ds_read_b128 v[140:143], v209 offset:49152
	ds_read_b128 v[216:219], v209 offset:57344
	v_add_f32_e32 v65, v161, v65
	v_exp_f32_e32 v66, v66
	v_add_f32_e32 v65, v146, v65
	v_exp_f32_e32 v67, v67
	v_add_f32_e32 v65, v147, v65
	v_exp_f32_e32 v68, v68
	s_waitcnt lgkmcnt(2)
	v_mfma_f32_32x32x16_bf16 v[80:95], v[204:207], v[136:139], v[80:95]
	ds_read_b128 v[136:139], v210 offset:49152
	ds_read_b128 v[204:207], v210 offset:57344
	ds_read_b128 v[220:223], v211 offset:49152
	ds_read_b128 v[208:211], v211 offset:57344
	ds_read_b128 v[224:227], v212 offset:49152
	ds_read_b128 v[228:231], v212 offset:57344
	ds_read_b128 v[232:235], v213 offset:49152
	ds_read_b128 v[236:239], v213 offset:57344
	v_add_f32_e32 v65, v64, v65
	v_exp_f32_e32 v69, v69
	v_add_f32_e32 v65, v145, v65
	v_exp_f32_e32 v70, v70
	v_add_f32_e32 v65, v66, v65
	v_exp_f32_e32 v71, v71
	s_waitcnt lgkmcnt(9)
	v_mfma_f32_32x32x16_bf16 v[96:111], v[140:143], v[132:135], v[96:111]
	v_add_f32_e32 v65, v67, v65
	v_exp_f32_e32 v72, v72
	v_add_f32_e32 v65, v68, v65
	ds_read_b128 v[140:143], v214 offset:49152
	ds_read_b128 v[212:215], v214 offset:57344
	v_exp_f32_e32 v73, v73
	v_add_f32_e32 v65, v69, v65
	v_add_f32_e32 v65, v70, v65
	s_waitcnt lgkmcnt(10)
	v_mfma_f32_32x32x16_bf16 v[80:95], v[216:219], v[132:135], v[80:95]
	v_exp_f32_e32 v132, v74
	v_exp_f32_e32 v133, v75
	v_add_f32_e32 v65, v71, v65
	v_exp_f32_e32 v134, v76
	v_add_f32_e32 v65, v72, v65
	v_exp_f32_e32 v135, v77
	v_add_f32_e32 v65, v73, v65
	s_waitcnt lgkmcnt(9)
	v_mfma_f32_32x32x16_bf16 v[96:111], v[136:139], v[128:131], v[96:111]
	v_exp_f32_e32 v78, v78
	v_add_f32_e32 v65, v132, v65
	v_exp_f32_e32 v79, v79
	v_add_f32_e32 v65, v133, v65
	v_add_f32_e32 v65, v134, v65
	v_add_f32_e32 v65, v135, v65
	v_add_f32_e32 v65, v78, v65
	s_waitcnt lgkmcnt(8)
	v_mfma_f32_32x32x16_bf16 v[80:95], v[204:207], v[128:131], v[80:95]
	v_add_f32_e32 v65, v79, v65
	v_cvt_pk_bf16_f32 v74, v166, v167
	v_cvt_pk_bf16_f32 v75, v162, v163
	v_cvt_pk_bf16_f32 v76, v158, v159
	v_cvt_pk_bf16_f32 v77, v156, v157
	s_nop 0
	v_permlane32_swap_b32_e32 v74, v76
	s_waitcnt lgkmcnt(7)
	v_mfma_f32_32x32x16_bf16 v[96:111], v[220:223], v[124:127], v[96:111]
	v_permlane32_swap_b32_e32 v75, v77
	s_waitcnt lgkmcnt(6)
	v_mfma_f32_32x32x16_bf16 v[80:95], v[208:211], v[124:127], v[80:95]
	s_waitcnt lgkmcnt(5)
	v_mfma_f32_32x32x16_bf16 v[96:111], v[224:227], v[120:123], v[96:111]
	s_waitcnt lgkmcnt(4)
	v_mfma_f32_32x32x16_bf16 v[80:95], v[228:231], v[120:123], v[80:95]
	v_mov_b32_e32 v120, v65
	s_nop 1
	v_permlane32_swap_b32_e32 v65, v120
	v_cvt_pk_bf16_f32 v122, v168, v169
	v_cvt_pk_bf16_f32 v123, v164, v165
	v_cvt_pk_bf16_f32 v124, v160, v161
	v_cvt_pk_bf16_f32 v125, v146, v147
	s_waitcnt lgkmcnt(3)
	v_mfma_f32_32x32x16_bf16 v[96:111], v[232:235], v[116:119], v[96:111]
	v_permlane32_swap_b32_e32 v122, v124
	v_permlane32_swap_b32_e32 v123, v125
	s_waitcnt lgkmcnt(2)
	v_mfma_f32_32x32x16_bf16 v[80:95], v[236:239], v[116:119], v[80:95]
	v_cvt_pk_bf16_f32 v116, v64, v145
	v_cvt_pk_bf16_f32 v117, v66, v67
	v_cvt_pk_bf16_f32 v118, v68, v69
	v_cvt_pk_bf16_f32 v119, v70, v71
	v_cvt_pk_bf16_f32 v126, v72, v73
	v_cvt_pk_bf16_f32 v127, v132, v133
	v_cvt_pk_bf16_f32 v128, v134, v135
	s_waitcnt lgkmcnt(1)
; #define MFMA32(a, b, c) __builtin_amdgcn_mfma_f32_32x32x16_bf16((a), (b), (c), 0, 0, 0)
; #define SBAR() __builtin_amdgcn_sched_barrier(0)
; template <int OFF> DI s16x4 tr_read(int vb) { s16x4 r; asm volatile("ds_read_b64_tr_b16 %0, %1 offset:%2" : "=&v"(r) : "v"(vb), "i"(OFF) : "memory"); return r; }
; template <int D0> DI void pv_one(f32x16& od, int vb, bf16x8 pa0, bf16x8 pa1, bf16x8 pa2, bf16x8 pa3) {
;     const s16x4 l0 = tr_read<v_rd_off(D0, 0, 0)>(vb), h0 = tr_read<v_rd_off(D0, 0, 1)>(vb), l1 = tr_read<v_rd_off(D0, 1, 0)>(vb), h1 = tr_read<v_rd_off(D0, 1, 1)>(vb);
;     const s16x4 l2 = tr_read<v_rd_off(D0, 2, 0)>(vb), h2 = tr_read<v_rd_off(D0, 2, 1)>(vb), l3 = tr_read<v_rd_off(D0, 3, 0)>(vb), h3 = tr_read<v_rd_off(D0, 3, 1)>(vb);
;     asm volatile("s_waitcnt lgkmcnt(0)" ::: "memory"); SBAR();
;     ...
;     od = MFMA32(pa0, PK(l0, h0), od);
;     od = MFMA32(pa1, PK(l1, h1), od);
;     od = MFMA32(pa2, PK(l2, h2), od);
;     od = MFMA32(pa3, PK(l3, h3), od);
;     ...
; }
; DI float pv_d0_sm(f32x16* o, int vb, bf16x8 pa0, bf16x8 pa1, bf16x8 pa2, bf16x8 pa3, f32x16& q0, f32x16& q1) {
;     pv_one<0>(o[0], vb, pa0, pa1, pa2, pa3); const float mx0 = smA_max0(q0);
;     pv_one<1>(o[1], vb, pa0, pa1, pa2, pa3); const float pmax = smA_max1(mx0, q1);
;     pv_one<2>(o[2], vb, pa0, pa1, pa2, pa3); smA_exp<0>(q0);
;     pv_one<3>(o[3], vb, pa0, pa1, pa2, pa3); smA_exp<8>(q0);
;     return pmax;
; }
; DI void attn_unit(const bf16_t* __restrict__ Qb, const bf16_t* __restrict__ Kh, const bf16_t* __restrict__ Vh, bf16_t* __restrict__ Ob, const float* __restrict__ onw, int seq, char* lds) {
;     ...
;     finishSM(pA0, pA1, alA, l_reg, pa0, pa1, pa2, pa3); SBAR();
;     { const float pm = pv_d0_sm(o, vb0, pa0, pa1, pa2, pa3, pB0, pB1); smB<false>(pB0, pB1, pm, m_reg, alB); }
	v_mfma_f32_32x32x16_bf16 v[96:111], v[140:143], v[112:115], v[96:111]
	v_cvt_pk_bf16_f32 v129, v78, v79
	v_permlane32_swap_b32_e32 v116, v118
	v_permlane32_swap_b32_e32 v117, v119
	v_permlane32_swap_b32_e32 v126, v128
	s_waitcnt lgkmcnt(0)
	v_mfma_f32_32x32x16_bf16 v[80:95], v[212:215], v[112:115], v[80:95]
	v_permlane32_swap_b32_e32 v127, v129
	ds_read_b64_tr_b16 v[66:67], v175 offset:0
	ds_read_b64_tr_b16 v[68:69], v175 offset:0x800
	ds_read_b64_tr_b16 v[70:71], v175 offset:0x1000
	ds_read_b64_tr_b16 v[72:73], v175 offset:0x1800
	ds_read_b64_tr_b16 v[112:113], v175 offset:0x2000
	ds_read_b64_tr_b16 v[114:115], v175 offset:0x2800
	ds_read_b64_tr_b16 v[130:131], v175 offset:0x3000
	ds_read_b64_tr_b16 v[132:133], v175 offset:0x3800
	s_waitcnt lgkmcnt(0)
	s_nop 0
	v_mfma_f32_32x32x16_bf16 v[0:15], v[74:77], v[66:69], v[0:15]
	s_nop 3
	v_max_f32_e32 v64, v97, v97
	v_max_f32_e32 v66, v96, v96
	v_max_f32_e32 v64, v66, v64
	ds_read_b64_tr_b16 v[66:67], v175 offset:0x200
	ds_read_b64_tr_b16 v[68:69], v175 offset:0xa00
	v_max3_f32 v64, v64, v98, v99
	v_max3_f32 v64, v64, v100, v101
	v_mfma_f32_32x32x16_bf16 v[0:15], v[122:125], v[70:73], v[0:15]
	ds_read_b64_tr_b16 v[70:71], v175 offset:0x1200
	ds_read_b64_tr_b16 v[72:73], v175 offset:0x1a00
	ds_read_b64_tr_b16 v[134:135], v175 offset:0x2200
	ds_read_b64_tr_b16 v[136:137], v175 offset:0x2a00
	v_max3_f32 v64, v64, v102, v103
	ds_read_b64_tr_b16 v[138:139], v175 offset:0x3200
	v_max3_f32 v64, v64, v104, v105
	v_mfma_f32_32x32x16_bf16 v[0:15], v[116:119], v[112:115], v[0:15]
	ds_read_b64_tr_b16 v[140:141], v175 offset:0x3a00
	v_max3_f32 v64, v64, v106, v107
	s_waitcnt lgkmcnt(0)
	v_max3_f32 v64, v64, v108, v109
	v_max3_f32 v64, v64, v110, v111
	v_mfma_f32_32x32x16_bf16 v[0:15], v[126:129], v[130:133], v[0:15]
	v_mfma_f32_32x32x16_bf16 v[48:63], v[74:77], v[66:69], v[48:63]
	v_max3_f32 v64, v64, v80, v81
	v_max3_f32 v64, v64, v82, v83
	v_max3_f32 v64, v64, v84, v85
	v_max3_f32 v64, v64, v86, v87
	v_max3_f32 v64, v64, v88, v89
	v_max3_f32 v64, v64, v90, v91
	v_max3_f32 v64, v64, v92, v93
	v_mfma_f32_32x32x16_bf16 v[48:63], v[122:125], v[70:73], v[48:63]
	v_max3_f32 v64, v64, v94, v95
	v_mov_b32_e32 v66, v64
	s_nop 1
	v_permlane32_swap_b32_e32 v64, v66
	v_max_f32_e32 v66, v66, v66
	v_max_f32_e32 v64, v64, v64
	v_max_f32_e32 v112, v64, v66
	v_mfma_f32_32x32x16_bf16 v[48:63], v[116:119], v[134:137], v[48:63]
	ds_read_b64_tr_b16 v[66:67], v175 offset:0x400
	ds_read_b64_tr_b16 v[68:69], v175 offset:0xc00
	ds_read_b64_tr_b16 v[130:131], v175 offset:0x1400
	ds_read_b64_tr_b16 v[132:133], v175 offset:0x1c00
	ds_read_b64_tr_b16 v[134:135], v175 offset:0x2400
	ds_read_b64_tr_b16 v[136:137], v175 offset:0x2c00
	ds_read_b64_tr_b16 v[156:157], v175 offset:0x3400
	v_mfma_f32_32x32x16_bf16 v[48:63], v[126:129], v[138:141], v[48:63]
	ds_read_b64_tr_b16 v[158:159], v175 offset:0x3c00
	s_waitcnt lgkmcnt(0)
	v_mfma_f32_32x32x16_bf16 v[16:31], v[74:77], v[66:69], v[16:31]
	v_exp_f32_e32 v70, v96
	v_exp_f32_e32 v71, v97
	ds_read_b64_tr_b16 v[96:97], v175 offset:0x600
	v_exp_f32_e32 v72, v98
	v_exp_f32_e32 v73, v99
	ds_read_b64_tr_b16 v[98:99], v175 offset:0xe00
	v_exp_f32_e32 v68, v100
	v_mfma_f32_32x32x16_bf16 v[16:31], v[122:125], v[130:133], v[16:31]
	v_exp_f32_e32 v69, v101
	ds_read_b64_tr_b16 v[100:101], v175 offset:0x1600
	v_exp_f32_e32 v66, v102
	v_exp_f32_e32 v67, v103
	ds_read_b64_tr_b16 v[102:103], v175 offset:0x1e00
	ds_read_b64_tr_b16 v[130:131], v175 offset:0x2600
	ds_read_b64_tr_b16 v[132:133], v175 offset:0x2e00
	v_mfma_f32_32x32x16_bf16 v[16:31], v[116:119], v[134:137], v[16:31]
	ds_read_b64_tr_b16 v[134:135], v175 offset:0x3600
	ds_read_b64_tr_b16 v[136:137], v175 offset:0x3e00
	s_waitcnt lgkmcnt(0)
	v_mfma_f32_32x32x16_bf16 v[16:31], v[126:129], v[156:159], v[16:31]
	v_mfma_f32_32x32x16_bf16 v[32:47], v[74:77], v[96:99], v[32:47]
	v_exp_f32_e32 v96, v104
	v_exp_f32_e32 v97, v105
	v_exp_f32_e32 v76, v106
	v_exp_f32_e32 v77, v107
	v_exp_f32_e32 v78, v108
	v_exp_f32_e32 v79, v109
	v_exp_f32_e32 v74, v110
	v_mfma_f32_32x32x16_bf16 v[32:47], v[122:125], v[100:103], v[32:47]
	v_exp_f32_e32 v75, v111
	v_cmp_ge_f32_e32 vcc, s82, v112
	v_mov_b32_e32 v64, 1.0
	s_cmp_eq_u64 vcc, exec
	v_mfma_f32_32x32x16_bf16 v[32:47], v[116:119], v[130:133], v[32:47]
	v_mfma_f32_32x32x16_bf16 v[32:47], v[126:129], v[134:137], v[32:47]
	s_cbranch_scc0 .LBB0_638
